# P15 panel hand-off: partial row sums stored write-through (sc1), the per-workgroup L2 write-back before the counter dropped
# speedup vs baseline: 1.0018x; 1.0018x over previous
.LBB0_1532:
	s_or_b64 exec, exec, s[0:1]
	s_add_u32 s4, s6, 0x1000000
	s_addc_u32 s5, s7, 0
	s_andn2_b32 s15, s15, 63
	v_add_u32_e32 v36, s15, v162
	s_movk_i32 s0, 0x100
	v_cmp_gt_i32_e32 vcc, s0, v36
	s_waitcnt lgkmcnt(0)
	s_barrier
	s_and_saveexec_b64 s[0:1], vcc
	s_cbranch_execz .LBB0_1534
	v_lshl_add_u32 v37, v36, 4, 0
	ds_read_b128 v[136:139], v37
	v_add_u32_e32 v36, s16, v36
	v_ashrrev_i32_e32 v37, 31, v36
	s_ashr_i32 s15, s14, 31
	v_lshl_add_u64 v[36:37], v[36:37], 4, s[4:5]
	s_waitcnt lgkmcnt(0)
	v_mov_b32_e32 v38, v137
	v_mov_b32_e32 v39, v138
	v_mov_b32_e32 v137, v139
	v_pk_add_f32 v[38:39], v[38:39], v[136:137]
	v_lshl_add_u64 v[36:37], s[14:15], 2, v[36:37]
	v_add_f32_e32 v38, v38, v39
	global_store_dword v[36:37], v38, off sc1
.LBB0_1534:
	s_or_b64 exec, exec, s[0:1]
	s_waitcnt vmcnt(0)
	v_or_b32_e32 v36, s33, v162
	v_cmp_eq_u32_e32 vcc, 0, v36
	s_barrier
	s_and_saveexec_b64 s[0:1], vcc
	s_cbranch_execz .LBB0_1546
	s_lshl_b32 s12, s12, 6
	s_ashr_i32 s13, s12, 31
	s_lshl_b64 s[12:13], s[12:13], 2
	s_mov_b64 s[8:9], exec
	s_add_u32 s6, s6, s12
	s_nop 0
	s_waitcnt vmcnt(0)
	s_waitcnt vmcnt(0)
	s_addc_u32 s7, s7, s13
	v_mbcnt_lo_u32_b32 v36, s8, 0
	s_add_u32 s6, s6, 0x1e04000
	v_mbcnt_hi_u32_b32 v36, s9, v36
	s_addc_u32 s7, s7, 0
	v_cmp_eq_u32_e32 vcc, 0, v36
	s_and_saveexec_b64 s[12:13], vcc
	s_cbranch_execz .LBB0_1537
	s_bcnt1_i32_b64 s8, s[8:9]
	v_mov_b32_e32 v36, 0
	v_mov_b32_e32 v37, s8
	global_atomic_add v36, v37, s[6:7]
